# conv item: batch the 62 serialized gate/value loads into 2 round trips (register staging), same math
# speedup vs baseline: 1.0180x; 1.0180x over previous
.LBB0_293:
	s_add_i32 s0, s40, 0xfffffa00
	s_lshl_b32 s2, s0, 5
	s_cmpk_lt_u32 s0, 0x100
	s_movk_i32 s0, 0x1f00
	s_cselect_b32 s1, s0, 0x3000
	s_movk_i32 s0, 0xfe0
	v_mov_b32_e32 v2, v218
	s_cselect_b32 s3, 0xe0, s0
	s_movk_i32 s0, 0x1000
	v_readlane_b32 s6, v251, 21
	s_cselect_b32 s0, 0x100, s0
	s_and_b32 s1, s1, s2
	s_and_b32 s2, s3, s2
	v_lshlrev_b32_e32 v0, 2, v2
	v_ashrrev_i32_e32 v3, 31, v2
	s_mov_b32 s3, 0
	v_readlane_b32 s7, v251, 22
	v_lshlrev_b32_e32 v4, 1, v2
	v_readlane_b32 s4, v251, 23
	v_readlane_b32 s5, v251, 24
	s_add_i32 s98, s1, s2
	s_add_i32 s98, s98, -15
	s_ashr_i32 s99, s98, 31
	s_lshl_b64 s[98:99], s[98:99], 9
	s_add_u32 s4, s4, s98
	s_addc_u32 s5, s5, s99
	s_add_u32 s98, s6, s98
	s_addc_u32 s99, s7, s99
	v_mov_b32_e32 v6, 0
	v_mov_b32_e32 v37, 0
	v_mov_b32_e32 v7, 0
	v_mov_b32_e32 v38, 0
	v_mov_b32_e32 v8, 0
	v_mov_b32_e32 v39, 0
	v_mov_b32_e32 v9, 0
	v_mov_b32_e32 v40, 0
	v_mov_b32_e32 v10, 0
	v_mov_b32_e32 v41, 0
	v_mov_b32_e32 v11, 0
	v_mov_b32_e32 v42, 0
	v_mov_b32_e32 v12, 0
	v_mov_b32_e32 v43, 0
	v_mov_b32_e32 v13, 0
	v_mov_b32_e32 v44, 0
	v_mov_b32_e32 v14, 0
	v_mov_b32_e32 v45, 0
	v_mov_b32_e32 v15, 0
	v_mov_b32_e32 v46, 0
	v_mov_b32_e32 v16, 0
	v_mov_b32_e32 v47, 0
	v_mov_b32_e32 v17, 0
	v_mov_b32_e32 v48, 0
	v_mov_b32_e32 v18, 0
	v_mov_b32_e32 v49, 0
	v_mov_b32_e32 v19, 0
	v_mov_b32_e32 v50, 0
	v_mov_b32_e32 v20, 0
	v_mov_b32_e32 v51, 0
	v_mov_b32_e32 v21, 0
	v_mov_b32_e32 v52, 0
	v_mov_b32_e32 v22, 0
	v_mov_b32_e32 v53, 0
	v_mov_b32_e32 v23, 0
	v_mov_b32_e32 v54, 0
	v_mov_b32_e32 v24, 0
	v_mov_b32_e32 v55, 0
	v_mov_b32_e32 v25, 0
	v_mov_b32_e32 v56, 0
	v_mov_b32_e32 v26, 0
	v_mov_b32_e32 v57, 0
	v_mov_b32_e32 v27, 0
	v_mov_b32_e32 v58, 0
	v_mov_b32_e32 v28, 0
	v_mov_b32_e32 v59, 0
	v_mov_b32_e32 v29, 0
	v_mov_b32_e32 v60, 0
	v_mov_b32_e32 v30, 0
	v_mov_b32_e32 v61, 0
	v_mov_b32_e32 v31, 0
	v_mov_b32_e32 v62, 0
	v_mov_b32_e32 v32, 0
	v_mov_b32_e32 v63, 0
	v_mov_b32_e32 v33, 0
	v_mov_b32_e32 v64, 0
	v_mov_b32_e32 v34, 0
	v_mov_b32_e32 v65, 0
	v_mov_b32_e32 v35, 0
	v_mov_b32_e32 v66, 0
	v_mov_b32_e32 v36, 0
	v_mov_b32_e32 v67, 0
	s_add_i32 s3, s2, -15
	s_cmp_ge_u32 s3, s0
	s_cbranch_scc1 .Lcv_skip_0
	global_load_ushort v6, v4, s[98:99]
	global_load_ushort v37, v4, s[4:5]
.Lcv_skip_0:
	s_add_i32 s3, s2, -14
	s_cmp_ge_u32 s3, s0
	s_cbranch_scc1 .Lcv_skip_1
	global_load_ushort v7, v4, s[98:99] offset:512
	global_load_ushort v38, v4, s[4:5] offset:512
.Lcv_skip_1:
	s_add_i32 s3, s2, -13
	s_cmp_ge_u32 s3, s0
	s_cbranch_scc1 .Lcv_skip_2
	global_load_ushort v8, v4, s[98:99] offset:1024
	global_load_ushort v39, v4, s[4:5] offset:1024
.Lcv_skip_2:
	s_add_i32 s3, s2, -12
	s_cmp_ge_u32 s3, s0
	s_cbranch_scc1 .Lcv_skip_3
	global_load_ushort v9, v4, s[98:99] offset:1536
	global_load_ushort v40, v4, s[4:5] offset:1536
.Lcv_skip_3:
	s_add_i32 s3, s2, -11
	s_cmp_ge_u32 s3, s0
	s_cbranch_scc1 .Lcv_skip_4
	global_load_ushort v10, v4, s[98:99] offset:2048
	global_load_ushort v41, v4, s[4:5] offset:2048
.Lcv_skip_4:
	s_add_i32 s3, s2, -10
	s_cmp_ge_u32 s3, s0
	s_cbranch_scc1 .Lcv_skip_5
	global_load_ushort v11, v4, s[98:99] offset:2560
	global_load_ushort v42, v4, s[4:5] offset:2560
.Lcv_skip_5:
	s_add_i32 s3, s2, -9
	s_cmp_ge_u32 s3, s0
	s_cbranch_scc1 .Lcv_skip_6
	global_load_ushort v12, v4, s[98:99] offset:3072
	global_load_ushort v43, v4, s[4:5] offset:3072
.Lcv_skip_6:
	s_add_i32 s3, s2, -8
	s_cmp_ge_u32 s3, s0
	s_cbranch_scc1 .Lcv_skip_7
	global_load_ushort v13, v4, s[98:99] offset:3584
	global_load_ushort v44, v4, s[4:5] offset:3584
.Lcv_skip_7:
	s_add_u32 s98, s98, 0x1000
	s_addc_u32 s99, s99, 0
	s_add_u32 s4, s4, 0x1000
	s_addc_u32 s5, s5, 0
	s_add_i32 s3, s2, -7
	s_cmp_ge_u32 s3, s0
	s_cbranch_scc1 .Lcv_skip_8
	global_load_ushort v14, v4, s[98:99]
	global_load_ushort v45, v4, s[4:5]
.Lcv_skip_8:
	s_add_i32 s3, s2, -6
	s_cmp_ge_u32 s3, s0
	s_cbranch_scc1 .Lcv_skip_9
	global_load_ushort v15, v4, s[98:99] offset:512
	global_load_ushort v46, v4, s[4:5] offset:512
.Lcv_skip_9:
	s_add_i32 s3, s2, -5
	s_cmp_ge_u32 s3, s0
	s_cbranch_scc1 .Lcv_skip_10
	global_load_ushort v16, v4, s[98:99] offset:1024
	global_load_ushort v47, v4, s[4:5] offset:1024
.Lcv_skip_10:
	s_add_i32 s3, s2, -4
	s_cmp_ge_u32 s3, s0
	s_cbranch_scc1 .Lcv_skip_11
	global_load_ushort v17, v4, s[98:99] offset:1536
	global_load_ushort v48, v4, s[4:5] offset:1536
.Lcv_skip_11:
	s_add_i32 s3, s2, -3
	s_cmp_ge_u32 s3, s0
	s_cbranch_scc1 .Lcv_skip_12
	global_load_ushort v18, v4, s[98:99] offset:2048
	global_load_ushort v49, v4, s[4:5] offset:2048
.Lcv_skip_12:
	s_add_i32 s3, s2, -2
	s_cmp_ge_u32 s3, s0
	s_cbranch_scc1 .Lcv_skip_13
	global_load_ushort v19, v4, s[98:99] offset:2560
	global_load_ushort v50, v4, s[4:5] offset:2560
.Lcv_skip_13:
	s_add_i32 s3, s2, -1
	s_cmp_ge_u32 s3, s0
	s_cbranch_scc1 .Lcv_skip_14
	global_load_ushort v20, v4, s[98:99] offset:3072
	global_load_ushort v51, v4, s[4:5] offset:3072
.Lcv_skip_14:
	s_add_i32 s3, s2, 0
	s_cmp_ge_u32 s3, s0
	s_cbranch_scc1 .Lcv_skip_15
	global_load_ushort v21, v4, s[98:99] offset:3584
	global_load_ushort v52, v4, s[4:5] offset:3584
.Lcv_skip_15:
	s_add_u32 s98, s98, 0x1000
	s_addc_u32 s99, s99, 0
	s_add_u32 s4, s4, 0x1000
	s_addc_u32 s5, s5, 0
	s_add_i32 s3, s2, 1
	s_cmp_ge_u32 s3, s0
	s_cbranch_scc1 .Lcv_skip_16
	global_load_ushort v22, v4, s[98:99]
	global_load_ushort v53, v4, s[4:5]
.Lcv_skip_16:
	s_add_i32 s3, s2, 2
	s_cmp_ge_u32 s3, s0
	s_cbranch_scc1 .Lcv_skip_17
	global_load_ushort v23, v4, s[98:99] offset:512
	global_load_ushort v54, v4, s[4:5] offset:512
.Lcv_skip_17:
	s_add_i32 s3, s2, 3
	s_cmp_ge_u32 s3, s0
	s_cbranch_scc1 .Lcv_skip_18
	global_load_ushort v24, v4, s[98:99] offset:1024
	global_load_ushort v55, v4, s[4:5] offset:1024
.Lcv_skip_18:
	s_add_i32 s3, s2, 4
	s_cmp_ge_u32 s3, s0
	s_cbranch_scc1 .Lcv_skip_19
	global_load_ushort v25, v4, s[98:99] offset:1536
	global_load_ushort v56, v4, s[4:5] offset:1536
.Lcv_skip_19:
	s_add_i32 s3, s2, 5
	s_cmp_ge_u32 s3, s0
	s_cbranch_scc1 .Lcv_skip_20
	global_load_ushort v26, v4, s[98:99] offset:2048
	global_load_ushort v57, v4, s[4:5] offset:2048
.Lcv_skip_20:
	s_add_i32 s3, s2, 6
	s_cmp_ge_u32 s3, s0
	s_cbranch_scc1 .Lcv_skip_21
	global_load_ushort v27, v4, s[98:99] offset:2560
	global_load_ushort v58, v4, s[4:5] offset:2560
.Lcv_skip_21:
	s_add_i32 s3, s2, 7
	s_cmp_ge_u32 s3, s0
	s_cbranch_scc1 .Lcv_skip_22
	global_load_ushort v28, v4, s[98:99] offset:3072
	global_load_ushort v59, v4, s[4:5] offset:3072
.Lcv_skip_22:
	s_add_i32 s3, s2, 8
	s_cmp_ge_u32 s3, s0
	s_cbranch_scc1 .Lcv_skip_23
	global_load_ushort v29, v4, s[98:99] offset:3584
	global_load_ushort v60, v4, s[4:5] offset:3584
.Lcv_skip_23:
	s_add_u32 s98, s98, 0x1000
	s_addc_u32 s99, s99, 0
	s_add_u32 s4, s4, 0x1000
	s_addc_u32 s5, s5, 0
	s_add_i32 s3, s2, 9
	s_cmp_ge_u32 s3, s0
	s_cbranch_scc1 .Lcv_skip_24
	global_load_ushort v30, v4, s[98:99]
	global_load_ushort v61, v4, s[4:5]
.Lcv_skip_24:
	s_add_i32 s3, s2, 10
	s_cmp_ge_u32 s3, s0
	s_cbranch_scc1 .Lcv_skip_25
	global_load_ushort v31, v4, s[98:99] offset:512
	global_load_ushort v62, v4, s[4:5] offset:512
.Lcv_skip_25:
	s_add_i32 s3, s2, 11
	s_cmp_ge_u32 s3, s0
	s_cbranch_scc1 .Lcv_skip_26
	global_load_ushort v32, v4, s[98:99] offset:1024
	global_load_ushort v63, v4, s[4:5] offset:1024
.Lcv_skip_26:
	s_add_i32 s3, s2, 12
	s_cmp_ge_u32 s3, s0
	s_cbranch_scc1 .Lcv_skip_27
	global_load_ushort v33, v4, s[98:99] offset:1536
	global_load_ushort v64, v4, s[4:5] offset:1536
.Lcv_skip_27:
	s_add_i32 s3, s2, 13
	s_cmp_ge_u32 s3, s0
	s_cbranch_scc1 .Lcv_skip_28
	global_load_ushort v34, v4, s[98:99] offset:2048
	global_load_ushort v65, v4, s[4:5] offset:2048
.Lcv_skip_28:
	s_add_i32 s3, s2, 14
	s_cmp_ge_u32 s3, s0
	s_cbranch_scc1 .Lcv_skip_29
	global_load_ushort v35, v4, s[98:99] offset:2560
	global_load_ushort v66, v4, s[4:5] offset:2560
.Lcv_skip_29:
	s_add_i32 s3, s2, 15
	s_cmp_ge_u32 s3, s0
	s_cbranch_scc1 .Lcv_skip_30
	global_load_ushort v36, v4, s[98:99] offset:3072
	global_load_ushort v67, v4, s[4:5] offset:3072
.Lcv_skip_30:
	s_waitcnt vmcnt(0)
	v_lshlrev_b32_e32 v37, 16, v37
	v_mul_f32_e32 v37, 0xbfb8aa3b, v37
	v_exp_f32_e32 v37, v37
	v_lshlrev_b32_e32 v6, 16, v6
	v_add_f32_e32 v37, 1.0, v37
	v_rcp_f32_e32 v37, v37
	s_nop 0
	v_mul_f32_e32 v6, v37, v6
	ds_write_b32 v0, v6
	v_lshlrev_b32_e32 v38, 16, v38
	v_mul_f32_e32 v38, 0xbfb8aa3b, v38
	v_exp_f32_e32 v38, v38
	v_lshlrev_b32_e32 v7, 16, v7
	v_add_f32_e32 v38, 1.0, v38
	v_rcp_f32_e32 v38, v38
	s_nop 0
	v_mul_f32_e32 v7, v38, v7
	ds_write_b32 v0, v7 offset:1024
	v_lshlrev_b32_e32 v39, 16, v39
	v_mul_f32_e32 v39, 0xbfb8aa3b, v39
	v_exp_f32_e32 v39, v39
	v_lshlrev_b32_e32 v8, 16, v8
	v_add_f32_e32 v39, 1.0, v39
	v_rcp_f32_e32 v39, v39
	s_nop 0
	v_mul_f32_e32 v8, v39, v8
	ds_write_b32 v0, v8 offset:2048
	v_lshlrev_b32_e32 v40, 16, v40
	v_mul_f32_e32 v40, 0xbfb8aa3b, v40
	v_exp_f32_e32 v40, v40
	v_lshlrev_b32_e32 v9, 16, v9
	v_add_f32_e32 v40, 1.0, v40
	v_rcp_f32_e32 v40, v40
	s_nop 0
	v_mul_f32_e32 v9, v40, v9
	ds_write_b32 v0, v9 offset:3072
	v_lshlrev_b32_e32 v41, 16, v41
	v_mul_f32_e32 v41, 0xbfb8aa3b, v41
	v_exp_f32_e32 v41, v41
	v_lshlrev_b32_e32 v10, 16, v10
	v_add_f32_e32 v41, 1.0, v41
	v_rcp_f32_e32 v41, v41
	s_nop 0
	v_mul_f32_e32 v10, v41, v10
	ds_write_b32 v0, v10 offset:4096
	v_lshlrev_b32_e32 v42, 16, v42
	v_mul_f32_e32 v42, 0xbfb8aa3b, v42
	v_exp_f32_e32 v42, v42
	v_lshlrev_b32_e32 v11, 16, v11
	v_add_f32_e32 v42, 1.0, v42
	v_rcp_f32_e32 v42, v42
	s_nop 0
	v_mul_f32_e32 v11, v42, v11
	ds_write_b32 v0, v11 offset:5120
	v_lshlrev_b32_e32 v43, 16, v43
	v_mul_f32_e32 v43, 0xbfb8aa3b, v43
	v_exp_f32_e32 v43, v43
	v_lshlrev_b32_e32 v12, 16, v12
	v_add_f32_e32 v43, 1.0, v43
	v_rcp_f32_e32 v43, v43
	s_nop 0
	v_mul_f32_e32 v12, v43, v12
	ds_write_b32 v0, v12 offset:6144
	v_lshlrev_b32_e32 v44, 16, v44
	v_mul_f32_e32 v44, 0xbfb8aa3b, v44
	v_exp_f32_e32 v44, v44
	v_lshlrev_b32_e32 v13, 16, v13
	v_add_f32_e32 v44, 1.0, v44
	v_rcp_f32_e32 v44, v44
	s_nop 0
	v_mul_f32_e32 v13, v44, v13
	ds_write_b32 v0, v13 offset:7168
	v_lshlrev_b32_e32 v45, 16, v45
	v_mul_f32_e32 v45, 0xbfb8aa3b, v45
	v_exp_f32_e32 v45, v45
	v_lshlrev_b32_e32 v14, 16, v14
	v_add_f32_e32 v45, 1.0, v45
	v_rcp_f32_e32 v45, v45
	s_nop 0
	v_mul_f32_e32 v14, v45, v14
	ds_write_b32 v0, v14 offset:8192
	v_lshlrev_b32_e32 v46, 16, v46
	v_mul_f32_e32 v46, 0xbfb8aa3b, v46
	v_exp_f32_e32 v46, v46
	v_lshlrev_b32_e32 v15, 16, v15
	v_add_f32_e32 v46, 1.0, v46
	v_rcp_f32_e32 v46, v46
	s_nop 0
	v_mul_f32_e32 v15, v46, v15
	ds_write_b32 v0, v15 offset:9216
	v_lshlrev_b32_e32 v47, 16, v47
	v_mul_f32_e32 v47, 0xbfb8aa3b, v47
	v_exp_f32_e32 v47, v47
	v_lshlrev_b32_e32 v16, 16, v16
	v_add_f32_e32 v47, 1.0, v47
	v_rcp_f32_e32 v47, v47
	s_nop 0
	v_mul_f32_e32 v16, v47, v16
	ds_write_b32 v0, v16 offset:10240
	v_lshlrev_b32_e32 v48, 16, v48
	v_mul_f32_e32 v48, 0xbfb8aa3b, v48
	v_exp_f32_e32 v48, v48
	v_lshlrev_b32_e32 v17, 16, v17
	v_add_f32_e32 v48, 1.0, v48
	v_rcp_f32_e32 v48, v48
	s_nop 0
	v_mul_f32_e32 v17, v48, v17
	ds_write_b32 v0, v17 offset:11264
	v_lshlrev_b32_e32 v49, 16, v49
	v_mul_f32_e32 v49, 0xbfb8aa3b, v49
	v_exp_f32_e32 v49, v49
	v_lshlrev_b32_e32 v18, 16, v18
	v_add_f32_e32 v49, 1.0, v49
	v_rcp_f32_e32 v49, v49
	s_nop 0
	v_mul_f32_e32 v18, v49, v18
	ds_write_b32 v0, v18 offset:12288
	v_lshlrev_b32_e32 v50, 16, v50
	v_mul_f32_e32 v50, 0xbfb8aa3b, v50
	v_exp_f32_e32 v50, v50
	v_lshlrev_b32_e32 v19, 16, v19
	v_add_f32_e32 v50, 1.0, v50
	v_rcp_f32_e32 v50, v50
	s_nop 0
	v_mul_f32_e32 v19, v50, v19
	ds_write_b32 v0, v19 offset:13312
	v_lshlrev_b32_e32 v51, 16, v51
	v_mul_f32_e32 v51, 0xbfb8aa3b, v51
	v_exp_f32_e32 v51, v51
	v_lshlrev_b32_e32 v20, 16, v20
	v_add_f32_e32 v51, 1.0, v51
	v_rcp_f32_e32 v51, v51
	s_nop 0
	v_mul_f32_e32 v20, v51, v20
	ds_write_b32 v0, v20 offset:14336
	v_lshlrev_b32_e32 v52, 16, v52
	v_mul_f32_e32 v52, 0xbfb8aa3b, v52
	v_exp_f32_e32 v52, v52
	v_lshlrev_b32_e32 v21, 16, v21
	v_add_f32_e32 v52, 1.0, v52
	v_rcp_f32_e32 v52, v52
	s_nop 0
	v_mul_f32_e32 v21, v52, v21
	ds_write_b32 v0, v21 offset:15360
	v_lshlrev_b32_e32 v53, 16, v53
	v_mul_f32_e32 v53, 0xbfb8aa3b, v53
	v_exp_f32_e32 v53, v53
	v_lshlrev_b32_e32 v22, 16, v22
	v_add_f32_e32 v53, 1.0, v53
	v_rcp_f32_e32 v53, v53
	s_nop 0
	v_mul_f32_e32 v22, v53, v22
	ds_write_b32 v0, v22 offset:16384
	v_lshlrev_b32_e32 v54, 16, v54
	v_mul_f32_e32 v54, 0xbfb8aa3b, v54
	v_exp_f32_e32 v54, v54
	v_lshlrev_b32_e32 v23, 16, v23
	v_add_f32_e32 v54, 1.0, v54
	v_rcp_f32_e32 v54, v54
	s_nop 0
	v_mul_f32_e32 v23, v54, v23
	ds_write_b32 v0, v23 offset:17408
	v_lshlrev_b32_e32 v55, 16, v55
	v_mul_f32_e32 v55, 0xbfb8aa3b, v55
	v_exp_f32_e32 v55, v55
	v_lshlrev_b32_e32 v24, 16, v24
	v_add_f32_e32 v55, 1.0, v55
	v_rcp_f32_e32 v55, v55
	s_nop 0
	v_mul_f32_e32 v24, v55, v24
	ds_write_b32 v0, v24 offset:18432
	v_lshlrev_b32_e32 v56, 16, v56
	v_mul_f32_e32 v56, 0xbfb8aa3b, v56
	v_exp_f32_e32 v56, v56
	v_lshlrev_b32_e32 v25, 16, v25
	v_add_f32_e32 v56, 1.0, v56
	v_rcp_f32_e32 v56, v56
	s_nop 0
	v_mul_f32_e32 v25, v56, v25
	ds_write_b32 v0, v25 offset:19456
	v_lshlrev_b32_e32 v57, 16, v57
	v_mul_f32_e32 v57, 0xbfb8aa3b, v57
	v_exp_f32_e32 v57, v57
	v_lshlrev_b32_e32 v26, 16, v26
	v_add_f32_e32 v57, 1.0, v57
	v_rcp_f32_e32 v57, v57
	s_nop 0
	v_mul_f32_e32 v26, v57, v26
	ds_write_b32 v0, v26 offset:20480
	v_lshlrev_b32_e32 v58, 16, v58
	v_mul_f32_e32 v58, 0xbfb8aa3b, v58
	v_exp_f32_e32 v58, v58
	v_lshlrev_b32_e32 v27, 16, v27
	v_add_f32_e32 v58, 1.0, v58
	v_rcp_f32_e32 v58, v58
	s_nop 0
	v_mul_f32_e32 v27, v58, v27
	ds_write_b32 v0, v27 offset:21504
	v_lshlrev_b32_e32 v59, 16, v59
	v_mul_f32_e32 v59, 0xbfb8aa3b, v59
	v_exp_f32_e32 v59, v59
	v_lshlrev_b32_e32 v28, 16, v28
	v_add_f32_e32 v59, 1.0, v59
	v_rcp_f32_e32 v59, v59
	s_nop 0
	v_mul_f32_e32 v28, v59, v28
	ds_write_b32 v0, v28 offset:22528
	v_lshlrev_b32_e32 v60, 16, v60
	v_mul_f32_e32 v60, 0xbfb8aa3b, v60
	v_exp_f32_e32 v60, v60
	v_lshlrev_b32_e32 v29, 16, v29
	v_add_f32_e32 v60, 1.0, v60
	v_rcp_f32_e32 v60, v60
	s_nop 0
	v_mul_f32_e32 v29, v60, v29
	ds_write_b32 v0, v29 offset:23552
	v_lshlrev_b32_e32 v61, 16, v61
	v_mul_f32_e32 v61, 0xbfb8aa3b, v61
	v_exp_f32_e32 v61, v61
	v_lshlrev_b32_e32 v30, 16, v30
	v_add_f32_e32 v61, 1.0, v61
	v_rcp_f32_e32 v61, v61
	s_nop 0
	v_mul_f32_e32 v30, v61, v30
	ds_write_b32 v0, v30 offset:24576
	v_lshlrev_b32_e32 v62, 16, v62
	v_mul_f32_e32 v62, 0xbfb8aa3b, v62
	v_exp_f32_e32 v62, v62
	v_lshlrev_b32_e32 v31, 16, v31
	v_add_f32_e32 v62, 1.0, v62
	v_rcp_f32_e32 v62, v62
	s_nop 0
	v_mul_f32_e32 v31, v62, v31
	ds_write_b32 v0, v31 offset:25600
	v_lshlrev_b32_e32 v63, 16, v63
	v_mul_f32_e32 v63, 0xbfb8aa3b, v63
	v_exp_f32_e32 v63, v63
	v_lshlrev_b32_e32 v32, 16, v32
	v_add_f32_e32 v63, 1.0, v63
	v_rcp_f32_e32 v63, v63
	s_nop 0
	v_mul_f32_e32 v32, v63, v32
	ds_write_b32 v0, v32 offset:26624
	v_lshlrev_b32_e32 v64, 16, v64
	v_mul_f32_e32 v64, 0xbfb8aa3b, v64
	v_exp_f32_e32 v64, v64
	v_lshlrev_b32_e32 v33, 16, v33
	v_add_f32_e32 v64, 1.0, v64
	v_rcp_f32_e32 v64, v64
	s_nop 0
	v_mul_f32_e32 v33, v64, v33
	ds_write_b32 v0, v33 offset:27648
	v_lshlrev_b32_e32 v65, 16, v65
	v_mul_f32_e32 v65, 0xbfb8aa3b, v65
	v_exp_f32_e32 v65, v65
	v_lshlrev_b32_e32 v34, 16, v34
	v_add_f32_e32 v65, 1.0, v65
	v_rcp_f32_e32 v65, v65
	s_nop 0
	v_mul_f32_e32 v34, v65, v34
	ds_write_b32 v0, v34 offset:28672
	v_lshlrev_b32_e32 v66, 16, v66
	v_mul_f32_e32 v66, 0xbfb8aa3b, v66
	v_exp_f32_e32 v66, v66
	v_lshlrev_b32_e32 v35, 16, v35
	v_add_f32_e32 v66, 1.0, v66
	v_rcp_f32_e32 v66, v66
	s_nop 0
	v_mul_f32_e32 v35, v66, v35
	ds_write_b32 v0, v35 offset:29696
	v_lshlrev_b32_e32 v67, 16, v67
	v_mul_f32_e32 v67, 0xbfb8aa3b, v67
	v_exp_f32_e32 v67, v67
	v_lshlrev_b32_e32 v36, 16, v36
	v_add_f32_e32 v67, 1.0, v67
	v_rcp_f32_e32 v67, v67
	s_nop 0
	v_mul_f32_e32 v36, v67, v36
	ds_write_b32 v0, v36 offset:30720
	v_mov_b32_e32 v6, 0
	v_mov_b32_e32 v37, 0
	v_mov_b32_e32 v7, 0
	v_mov_b32_e32 v38, 0
	v_mov_b32_e32 v8, 0
	v_mov_b32_e32 v39, 0
	v_mov_b32_e32 v9, 0
	v_mov_b32_e32 v40, 0
	v_mov_b32_e32 v10, 0
	v_mov_b32_e32 v41, 0
	v_mov_b32_e32 v11, 0
	v_mov_b32_e32 v42, 0
	v_mov_b32_e32 v12, 0
	v_mov_b32_e32 v43, 0
	v_mov_b32_e32 v13, 0
	v_mov_b32_e32 v44, 0
	v_mov_b32_e32 v14, 0
	v_mov_b32_e32 v45, 0
	v_mov_b32_e32 v15, 0
	v_mov_b32_e32 v46, 0
	v_mov_b32_e32 v16, 0
	v_mov_b32_e32 v47, 0
	v_mov_b32_e32 v17, 0
	v_mov_b32_e32 v48, 0
	v_mov_b32_e32 v18, 0
	v_mov_b32_e32 v49, 0
	v_mov_b32_e32 v19, 0
	v_mov_b32_e32 v50, 0
	v_mov_b32_e32 v20, 0
	v_mov_b32_e32 v51, 0
	v_mov_b32_e32 v21, 0
	v_mov_b32_e32 v52, 0
	v_mov_b32_e32 v22, 0
	v_mov_b32_e32 v53, 0
	v_mov_b32_e32 v23, 0
	v_mov_b32_e32 v54, 0
	v_mov_b32_e32 v24, 0
	v_mov_b32_e32 v55, 0
	v_mov_b32_e32 v25, 0
	v_mov_b32_e32 v56, 0
	v_mov_b32_e32 v26, 0
	v_mov_b32_e32 v57, 0
	v_mov_b32_e32 v27, 0
	v_mov_b32_e32 v58, 0
	v_mov_b32_e32 v28, 0
	v_mov_b32_e32 v59, 0
	v_mov_b32_e32 v29, 0
	v_mov_b32_e32 v60, 0
	v_mov_b32_e32 v30, 0
	v_mov_b32_e32 v61, 0
	v_mov_b32_e32 v31, 0
	v_mov_b32_e32 v62, 0
	v_mov_b32_e32 v32, 0
	v_mov_b32_e32 v63, 0
	v_mov_b32_e32 v33, 0
	v_mov_b32_e32 v64, 0
	v_mov_b32_e32 v34, 0
	v_mov_b32_e32 v65, 0
	v_mov_b32_e32 v35, 0
	v_mov_b32_e32 v66, 0
	v_mov_b32_e32 v36, 0
	v_mov_b32_e32 v67, 0
	s_add_i32 s3, s2, 16
	s_cmp_ge_u32 s3, s0
	s_cbranch_scc1 .Lcv_skip_31
	global_load_ushort v6, v4, s[98:99] offset:3584
	global_load_ushort v37, v4, s[4:5] offset:3584
.Lcv_skip_31:
	s_add_u32 s98, s98, 0x1000
	s_addc_u32 s99, s99, 0
	s_add_u32 s4, s4, 0x1000
	s_addc_u32 s5, s5, 0
	s_add_i32 s3, s2, 17
	s_cmp_ge_u32 s3, s0
	s_cbranch_scc1 .Lcv_skip_32
	global_load_ushort v7, v4, s[98:99]
	global_load_ushort v38, v4, s[4:5]
.Lcv_skip_32:
	s_add_i32 s3, s2, 18
	s_cmp_ge_u32 s3, s0
	s_cbranch_scc1 .Lcv_skip_33
	global_load_ushort v8, v4, s[98:99] offset:512
	global_load_ushort v39, v4, s[4:5] offset:512
.Lcv_skip_33:
	s_add_i32 s3, s2, 19
	s_cmp_ge_u32 s3, s0
	s_cbranch_scc1 .Lcv_skip_34
	global_load_ushort v9, v4, s[98:99] offset:1024
	global_load_ushort v40, v4, s[4:5] offset:1024
.Lcv_skip_34:
	s_add_i32 s3, s2, 20
	s_cmp_ge_u32 s3, s0
	s_cbranch_scc1 .Lcv_skip_35
	global_load_ushort v10, v4, s[98:99] offset:1536
	global_load_ushort v41, v4, s[4:5] offset:1536
.Lcv_skip_35:
	s_add_i32 s3, s2, 21
	s_cmp_ge_u32 s3, s0
	s_cbranch_scc1 .Lcv_skip_36
	global_load_ushort v11, v4, s[98:99] offset:2048
	global_load_ushort v42, v4, s[4:5] offset:2048
.Lcv_skip_36:
	s_add_i32 s3, s2, 22
	s_cmp_ge_u32 s3, s0
	s_cbranch_scc1 .Lcv_skip_37
	global_load_ushort v12, v4, s[98:99] offset:2560
	global_load_ushort v43, v4, s[4:5] offset:2560
.Lcv_skip_37:
	s_add_i32 s3, s2, 23
	s_cmp_ge_u32 s3, s0
	s_cbranch_scc1 .Lcv_skip_38
	global_load_ushort v13, v4, s[98:99] offset:3072
	global_load_ushort v44, v4, s[4:5] offset:3072
.Lcv_skip_38:
	s_add_i32 s3, s2, 24
	s_cmp_ge_u32 s3, s0
	s_cbranch_scc1 .Lcv_skip_39
	global_load_ushort v14, v4, s[98:99] offset:3584
	global_load_ushort v45, v4, s[4:5] offset:3584
.Lcv_skip_39:
	s_add_u32 s98, s98, 0x1000
	s_addc_u32 s99, s99, 0
	s_add_u32 s4, s4, 0x1000
	s_addc_u32 s5, s5, 0
	s_add_i32 s3, s2, 25
	s_cmp_ge_u32 s3, s0
	s_cbranch_scc1 .Lcv_skip_40
	global_load_ushort v15, v4, s[98:99]
	global_load_ushort v46, v4, s[4:5]
.Lcv_skip_40:
	s_add_i32 s3, s2, 26
	s_cmp_ge_u32 s3, s0
	s_cbranch_scc1 .Lcv_skip_41
	global_load_ushort v16, v4, s[98:99] offset:512
	global_load_ushort v47, v4, s[4:5] offset:512
.Lcv_skip_41:
	s_add_i32 s3, s2, 27
	s_cmp_ge_u32 s3, s0
	s_cbranch_scc1 .Lcv_skip_42
	global_load_ushort v17, v4, s[98:99] offset:1024
	global_load_ushort v48, v4, s[4:5] offset:1024
.Lcv_skip_42:
	s_add_i32 s3, s2, 28
	s_cmp_ge_u32 s3, s0
	s_cbranch_scc1 .Lcv_skip_43
	global_load_ushort v18, v4, s[98:99] offset:1536
	global_load_ushort v49, v4, s[4:5] offset:1536
.Lcv_skip_43:
	s_add_i32 s3, s2, 29
	s_cmp_ge_u32 s3, s0
	s_cbranch_scc1 .Lcv_skip_44
	global_load_ushort v19, v4, s[98:99] offset:2048
	global_load_ushort v50, v4, s[4:5] offset:2048
.Lcv_skip_44:
	s_add_i32 s3, s2, 30
	s_cmp_ge_u32 s3, s0
	s_cbranch_scc1 .Lcv_skip_45
	global_load_ushort v20, v4, s[98:99] offset:2560
	global_load_ushort v51, v4, s[4:5] offset:2560
.Lcv_skip_45:
	s_add_i32 s3, s2, 31
	s_cmp_ge_u32 s3, s0
	s_cbranch_scc1 .Lcv_skip_46
	global_load_ushort v21, v4, s[98:99] offset:3072
	global_load_ushort v52, v4, s[4:5] offset:3072
.Lcv_skip_46:
	s_add_i32 s3, s2, 32
	s_cmp_ge_u32 s3, s0
	s_cbranch_scc1 .Lcv_skip_47
	global_load_ushort v22, v4, s[98:99] offset:3584
	global_load_ushort v53, v4, s[4:5] offset:3584
.Lcv_skip_47:
	s_add_u32 s98, s98, 0x1000
	s_addc_u32 s99, s99, 0
	s_add_u32 s4, s4, 0x1000
	s_addc_u32 s5, s5, 0
	s_add_i32 s3, s2, 33
	s_cmp_ge_u32 s3, s0
	s_cbranch_scc1 .Lcv_skip_48
	global_load_ushort v23, v4, s[98:99]
	global_load_ushort v54, v4, s[4:5]
.Lcv_skip_48:
	s_add_i32 s3, s2, 34
	s_cmp_ge_u32 s3, s0
	s_cbranch_scc1 .Lcv_skip_49
	global_load_ushort v24, v4, s[98:99] offset:512
	global_load_ushort v55, v4, s[4:5] offset:512
.Lcv_skip_49:
	s_add_i32 s3, s2, 35
	s_cmp_ge_u32 s3, s0
	s_cbranch_scc1 .Lcv_skip_50
	global_load_ushort v25, v4, s[98:99] offset:1024
	global_load_ushort v56, v4, s[4:5] offset:1024
.Lcv_skip_50:
	s_add_i32 s3, s2, 36
	s_cmp_ge_u32 s3, s0
	s_cbranch_scc1 .Lcv_skip_51
	global_load_ushort v26, v4, s[98:99] offset:1536
	global_load_ushort v57, v4, s[4:5] offset:1536
.Lcv_skip_51:
	s_add_i32 s3, s2, 37
	s_cmp_ge_u32 s3, s0
	s_cbranch_scc1 .Lcv_skip_52
	global_load_ushort v27, v4, s[98:99] offset:2048
	global_load_ushort v58, v4, s[4:5] offset:2048
.Lcv_skip_52:
	s_add_i32 s3, s2, 38
	s_cmp_ge_u32 s3, s0
	s_cbranch_scc1 .Lcv_skip_53
	global_load_ushort v28, v4, s[98:99] offset:2560
	global_load_ushort v59, v4, s[4:5] offset:2560
.Lcv_skip_53:
	s_add_i32 s3, s2, 39
	s_cmp_ge_u32 s3, s0
	s_cbranch_scc1 .Lcv_skip_54
	global_load_ushort v29, v4, s[98:99] offset:3072
	global_load_ushort v60, v4, s[4:5] offset:3072
.Lcv_skip_54:
	s_add_i32 s3, s2, 40
	s_cmp_ge_u32 s3, s0
	s_cbranch_scc1 .Lcv_skip_55
	global_load_ushort v30, v4, s[98:99] offset:3584
	global_load_ushort v61, v4, s[4:5] offset:3584
.Lcv_skip_55:
	s_add_u32 s98, s98, 0x1000
	s_addc_u32 s99, s99, 0
	s_add_u32 s4, s4, 0x1000
	s_addc_u32 s5, s5, 0
	s_add_i32 s3, s2, 41
	s_cmp_ge_u32 s3, s0
	s_cbranch_scc1 .Lcv_skip_56
	global_load_ushort v31, v4, s[98:99]
	global_load_ushort v62, v4, s[4:5]
.Lcv_skip_56:
	s_add_i32 s3, s2, 42
	s_cmp_ge_u32 s3, s0
	s_cbranch_scc1 .Lcv_skip_57
	global_load_ushort v32, v4, s[98:99] offset:512
	global_load_ushort v63, v4, s[4:5] offset:512
.Lcv_skip_57:
	s_add_i32 s3, s2, 43
	s_cmp_ge_u32 s3, s0
	s_cbranch_scc1 .Lcv_skip_58
	global_load_ushort v33, v4, s[98:99] offset:1024
	global_load_ushort v64, v4, s[4:5] offset:1024
.Lcv_skip_58:
	s_add_i32 s3, s2, 44
	s_cmp_ge_u32 s3, s0
	s_cbranch_scc1 .Lcv_skip_59
	global_load_ushort v34, v4, s[98:99] offset:1536
	global_load_ushort v65, v4, s[4:5] offset:1536
.Lcv_skip_59:
	s_add_i32 s3, s2, 45
	s_cmp_ge_u32 s3, s0
	s_cbranch_scc1 .Lcv_skip_60
	global_load_ushort v35, v4, s[98:99] offset:2048
	global_load_ushort v66, v4, s[4:5] offset:2048
.Lcv_skip_60:
	s_add_i32 s3, s2, 46
	s_cmp_ge_u32 s3, s0
	s_cbranch_scc1 .Lcv_skip_61
	global_load_ushort v36, v4, s[98:99] offset:2560
	global_load_ushort v67, v4, s[4:5] offset:2560
.Lcv_skip_61:
	s_waitcnt vmcnt(0)
	v_lshlrev_b32_e32 v37, 16, v37
	v_mul_f32_e32 v37, 0xbfb8aa3b, v37
	v_exp_f32_e32 v37, v37
	v_lshlrev_b32_e32 v6, 16, v6
	v_add_f32_e32 v37, 1.0, v37
	v_rcp_f32_e32 v37, v37
	s_nop 0
	v_mul_f32_e32 v6, v37, v6
	ds_write_b32 v0, v6 offset:31744
	v_lshlrev_b32_e32 v38, 16, v38
	v_mul_f32_e32 v38, 0xbfb8aa3b, v38
	v_exp_f32_e32 v38, v38
	v_lshlrev_b32_e32 v7, 16, v7
	v_add_f32_e32 v38, 1.0, v38
	v_rcp_f32_e32 v38, v38
	s_nop 0
	v_mul_f32_e32 v7, v38, v7
	ds_write_b32 v0, v7 offset:32768
	v_lshlrev_b32_e32 v39, 16, v39
	v_mul_f32_e32 v39, 0xbfb8aa3b, v39
	v_exp_f32_e32 v39, v39
	v_lshlrev_b32_e32 v8, 16, v8
	v_add_f32_e32 v39, 1.0, v39
	v_rcp_f32_e32 v39, v39
	s_nop 0
	v_mul_f32_e32 v8, v39, v8
	ds_write_b32 v0, v8 offset:33792
	v_lshlrev_b32_e32 v40, 16, v40
	v_mul_f32_e32 v40, 0xbfb8aa3b, v40
	v_exp_f32_e32 v40, v40
	v_lshlrev_b32_e32 v9, 16, v9
	v_add_f32_e32 v40, 1.0, v40
	v_rcp_f32_e32 v40, v40
	s_nop 0
	v_mul_f32_e32 v9, v40, v9
	ds_write_b32 v0, v9 offset:34816
	v_lshlrev_b32_e32 v41, 16, v41
	v_mul_f32_e32 v41, 0xbfb8aa3b, v41
	v_exp_f32_e32 v41, v41
	v_lshlrev_b32_e32 v10, 16, v10
	v_add_f32_e32 v41, 1.0, v41
	v_rcp_f32_e32 v41, v41
	s_nop 0
	v_mul_f32_e32 v10, v41, v10
	ds_write_b32 v0, v10 offset:35840
	v_lshlrev_b32_e32 v42, 16, v42
	v_mul_f32_e32 v42, 0xbfb8aa3b, v42
	v_exp_f32_e32 v42, v42
	v_lshlrev_b32_e32 v11, 16, v11
	v_add_f32_e32 v42, 1.0, v42
	v_rcp_f32_e32 v42, v42
	s_nop 0
	v_mul_f32_e32 v11, v42, v11
	ds_write_b32 v0, v11 offset:36864
	v_lshlrev_b32_e32 v43, 16, v43
	v_mul_f32_e32 v43, 0xbfb8aa3b, v43
	v_exp_f32_e32 v43, v43
	v_lshlrev_b32_e32 v12, 16, v12
	v_add_f32_e32 v43, 1.0, v43
	v_rcp_f32_e32 v43, v43
	s_nop 0
	v_mul_f32_e32 v12, v43, v12
	ds_write_b32 v0, v12 offset:37888
	v_lshlrev_b32_e32 v44, 16, v44
	v_mul_f32_e32 v44, 0xbfb8aa3b, v44
	v_exp_f32_e32 v44, v44
	v_lshlrev_b32_e32 v13, 16, v13
	v_add_f32_e32 v44, 1.0, v44
	v_rcp_f32_e32 v44, v44
	s_nop 0
	v_mul_f32_e32 v13, v44, v13
	ds_write_b32 v0, v13 offset:38912
	v_lshlrev_b32_e32 v45, 16, v45
	v_mul_f32_e32 v45, 0xbfb8aa3b, v45
	v_exp_f32_e32 v45, v45
	v_lshlrev_b32_e32 v14, 16, v14
	v_add_f32_e32 v45, 1.0, v45
	v_rcp_f32_e32 v45, v45
	s_nop 0
	v_mul_f32_e32 v14, v45, v14
	ds_write_b32 v0, v14 offset:39936
	v_lshlrev_b32_e32 v46, 16, v46
	v_mul_f32_e32 v46, 0xbfb8aa3b, v46
	v_exp_f32_e32 v46, v46
	v_lshlrev_b32_e32 v15, 16, v15
	v_add_f32_e32 v46, 1.0, v46
	v_rcp_f32_e32 v46, v46
	s_nop 0
	v_mul_f32_e32 v15, v46, v15
	ds_write_b32 v0, v15 offset:40960
	v_lshlrev_b32_e32 v47, 16, v47
	v_mul_f32_e32 v47, 0xbfb8aa3b, v47
	v_exp_f32_e32 v47, v47
	v_lshlrev_b32_e32 v16, 16, v16
	v_add_f32_e32 v47, 1.0, v47
	v_rcp_f32_e32 v47, v47
	s_nop 0
	v_mul_f32_e32 v16, v47, v16
	ds_write_b32 v0, v16 offset:41984
	v_lshlrev_b32_e32 v48, 16, v48
	v_mul_f32_e32 v48, 0xbfb8aa3b, v48
	v_exp_f32_e32 v48, v48
	v_lshlrev_b32_e32 v17, 16, v17
	v_add_f32_e32 v48, 1.0, v48
	v_rcp_f32_e32 v48, v48
	s_nop 0
	v_mul_f32_e32 v17, v48, v17
	ds_write_b32 v0, v17 offset:43008
	v_lshlrev_b32_e32 v49, 16, v49
	v_mul_f32_e32 v49, 0xbfb8aa3b, v49
	v_exp_f32_e32 v49, v49
	v_lshlrev_b32_e32 v18, 16, v18
	v_add_f32_e32 v49, 1.0, v49
	v_rcp_f32_e32 v49, v49
	s_nop 0
	v_mul_f32_e32 v18, v49, v18
	ds_write_b32 v0, v18 offset:44032
	v_lshlrev_b32_e32 v50, 16, v50
	v_mul_f32_e32 v50, 0xbfb8aa3b, v50
	v_exp_f32_e32 v50, v50
	v_lshlrev_b32_e32 v19, 16, v19
	v_add_f32_e32 v50, 1.0, v50
	v_rcp_f32_e32 v50, v50
	s_nop 0
	v_mul_f32_e32 v19, v50, v19
	ds_write_b32 v0, v19 offset:45056
	v_lshlrev_b32_e32 v51, 16, v51
	v_mul_f32_e32 v51, 0xbfb8aa3b, v51
	v_exp_f32_e32 v51, v51
	v_lshlrev_b32_e32 v20, 16, v20
	v_add_f32_e32 v51, 1.0, v51
	v_rcp_f32_e32 v51, v51
	s_nop 0
	v_mul_f32_e32 v20, v51, v20
	ds_write_b32 v0, v20 offset:46080
	v_lshlrev_b32_e32 v52, 16, v52
	v_mul_f32_e32 v52, 0xbfb8aa3b, v52
	v_exp_f32_e32 v52, v52
	v_lshlrev_b32_e32 v21, 16, v21
	v_add_f32_e32 v52, 1.0, v52
	v_rcp_f32_e32 v52, v52
	s_nop 0
	v_mul_f32_e32 v21, v52, v21
	ds_write_b32 v0, v21 offset:47104
	v_lshlrev_b32_e32 v53, 16, v53
	v_mul_f32_e32 v53, 0xbfb8aa3b, v53
	v_exp_f32_e32 v53, v53
	v_lshlrev_b32_e32 v22, 16, v22
	v_add_f32_e32 v53, 1.0, v53
	v_rcp_f32_e32 v53, v53
	s_nop 0
	v_mul_f32_e32 v22, v53, v22
	ds_write_b32 v0, v22 offset:48128
	v_lshlrev_b32_e32 v54, 16, v54
	v_mul_f32_e32 v54, 0xbfb8aa3b, v54
	v_exp_f32_e32 v54, v54
	v_lshlrev_b32_e32 v23, 16, v23
	v_add_f32_e32 v54, 1.0, v54
	v_rcp_f32_e32 v54, v54
	s_nop 0
	v_mul_f32_e32 v23, v54, v23
	ds_write_b32 v0, v23 offset:49152
	v_lshlrev_b32_e32 v55, 16, v55
	v_mul_f32_e32 v55, 0xbfb8aa3b, v55
	v_exp_f32_e32 v55, v55
	v_lshlrev_b32_e32 v24, 16, v24
	v_add_f32_e32 v55, 1.0, v55
	v_rcp_f32_e32 v55, v55
	s_nop 0
	v_mul_f32_e32 v24, v55, v24
	ds_write_b32 v0, v24 offset:50176
	v_lshlrev_b32_e32 v56, 16, v56
	v_mul_f32_e32 v56, 0xbfb8aa3b, v56
	v_exp_f32_e32 v56, v56
	v_lshlrev_b32_e32 v25, 16, v25
	v_add_f32_e32 v56, 1.0, v56
	v_rcp_f32_e32 v56, v56
	s_nop 0
	v_mul_f32_e32 v25, v56, v25
	ds_write_b32 v0, v25 offset:51200
	v_lshlrev_b32_e32 v57, 16, v57
	v_mul_f32_e32 v57, 0xbfb8aa3b, v57
	v_exp_f32_e32 v57, v57
	v_lshlrev_b32_e32 v26, 16, v26
	v_add_f32_e32 v57, 1.0, v57
	v_rcp_f32_e32 v57, v57
	s_nop 0
	v_mul_f32_e32 v26, v57, v26
	ds_write_b32 v0, v26 offset:52224
	v_lshlrev_b32_e32 v58, 16, v58
	v_mul_f32_e32 v58, 0xbfb8aa3b, v58
	v_exp_f32_e32 v58, v58
	v_lshlrev_b32_e32 v27, 16, v27
	v_add_f32_e32 v58, 1.0, v58
	v_rcp_f32_e32 v58, v58
	s_nop 0
	v_mul_f32_e32 v27, v58, v27
	ds_write_b32 v0, v27 offset:53248
	v_lshlrev_b32_e32 v59, 16, v59
	v_mul_f32_e32 v59, 0xbfb8aa3b, v59
	v_exp_f32_e32 v59, v59
	v_lshlrev_b32_e32 v28, 16, v28
	v_add_f32_e32 v59, 1.0, v59
	v_rcp_f32_e32 v59, v59
	s_nop 0
	v_mul_f32_e32 v28, v59, v28
	ds_write_b32 v0, v28 offset:54272
	v_lshlrev_b32_e32 v60, 16, v60
	v_mul_f32_e32 v60, 0xbfb8aa3b, v60
	v_exp_f32_e32 v60, v60
	v_lshlrev_b32_e32 v29, 16, v29
	v_add_f32_e32 v60, 1.0, v60
	v_rcp_f32_e32 v60, v60
	s_nop 0
	v_mul_f32_e32 v29, v60, v29
	ds_write_b32 v0, v29 offset:55296
	v_lshlrev_b32_e32 v61, 16, v61
	v_mul_f32_e32 v61, 0xbfb8aa3b, v61
	v_exp_f32_e32 v61, v61
	v_lshlrev_b32_e32 v30, 16, v30
	v_add_f32_e32 v61, 1.0, v61
	v_rcp_f32_e32 v61, v61
	s_nop 0
	v_mul_f32_e32 v30, v61, v30
	ds_write_b32 v0, v30 offset:56320
	v_lshlrev_b32_e32 v62, 16, v62
	v_mul_f32_e32 v62, 0xbfb8aa3b, v62
	v_exp_f32_e32 v62, v62
	v_lshlrev_b32_e32 v31, 16, v31
	v_add_f32_e32 v62, 1.0, v62
	v_rcp_f32_e32 v62, v62
	s_nop 0
	v_mul_f32_e32 v31, v62, v31
	ds_write_b32 v0, v31 offset:57344
	v_lshlrev_b32_e32 v63, 16, v63
	v_mul_f32_e32 v63, 0xbfb8aa3b, v63
	v_exp_f32_e32 v63, v63
	v_lshlrev_b32_e32 v32, 16, v32
	v_add_f32_e32 v63, 1.0, v63
	v_rcp_f32_e32 v63, v63
	s_nop 0
	v_mul_f32_e32 v32, v63, v32
	ds_write_b32 v0, v32 offset:58368
	v_lshlrev_b32_e32 v64, 16, v64
	v_mul_f32_e32 v64, 0xbfb8aa3b, v64
	v_exp_f32_e32 v64, v64
	v_lshlrev_b32_e32 v33, 16, v33
	v_add_f32_e32 v64, 1.0, v64
	v_rcp_f32_e32 v64, v64
	s_nop 0
	v_mul_f32_e32 v33, v64, v33
	ds_write_b32 v0, v33 offset:59392
	v_lshlrev_b32_e32 v65, 16, v65
	v_mul_f32_e32 v65, 0xbfb8aa3b, v65
	v_exp_f32_e32 v65, v65
	v_lshlrev_b32_e32 v34, 16, v34
	v_add_f32_e32 v65, 1.0, v65
	v_rcp_f32_e32 v65, v65
	s_nop 0
	v_mul_f32_e32 v34, v65, v34
	ds_write_b32 v0, v34 offset:60416
	v_lshlrev_b32_e32 v66, 16, v66
	v_mul_f32_e32 v66, 0xbfb8aa3b, v66
	v_exp_f32_e32 v66, v66
	v_lshlrev_b32_e32 v35, 16, v35
	v_add_f32_e32 v66, 1.0, v66
	v_rcp_f32_e32 v66, v66
	s_nop 0
	v_mul_f32_e32 v35, v66, v35
	ds_write_b32 v0, v35 offset:61440
	v_lshlrev_b32_e32 v67, 16, v67
	v_mul_f32_e32 v67, 0xbfb8aa3b, v67
	v_exp_f32_e32 v67, v67
	v_lshlrev_b32_e32 v36, 16, v36
	v_add_f32_e32 v67, 1.0, v67
	v_rcp_f32_e32 v67, v67
	s_nop 0
	v_mul_f32_e32 v36, v67, v36
	ds_write_b32 v0, v36 offset:62464
